# conv-tap staging at P2 start: three loads in flight instead of three serial round trips (now on each team's critical path after the P1|P2 seam)
# speedup vs baseline: 1.0058x; 1.0058x over previous
; #define GAS __attribute__((address_space(1)))
; #define LAS __attribute__((address_space(3)))
; __device__ __forceinline__ void dn_load_raw(DnRaw& R, int unit, const bf16_t* DNR, const bf16_t* HALO, const float* GBT, int tid) {
;     const bf16_t* region = DNR + (size_t)unit * 32768; const int rb = unit >> 2, h = unit & 3, n = rb & (NCH - 1), cg = tid & 15, t0 = 2 * (tid >> 4);
; #pragma unroll
;     for (int part = 0; part < 3; ++part)
; #pragma unroll
;         for (int j = 0; j < 5; ++j) { const int t = t0 - 3 + j; v4u w4 = (v4u){0u, 0u, 0u, 0u};
;             if (t >= 0) w4 = *(const GAS v4u*)(region + part * 8192 + t * 128 + 8 * cg);
;             else if (n != 0) w4 = *(const GAS v4u*)(HALO + (size_t)(rb - 1) * 4608 + (t + 3) * 1536 + h * 384 + part * 128 + 8 * cg);
;             R.w[part][j] = w4; }
;     R.be = 0.f; R.gg = 0.f;
;     if (tid < 64) { const int m = rb * 64 + tid; R.be = GBT[(size_t)m * 8 + h]; R.gg = GBT[(size_t)m * 8 + 4 + h]; }
; }
; __global__ void __launch_bounds__(NWAVES * 64, 2) fwd(Args args) {
;     ...
;             { const int h_ = (int)blockIdx.x & 3; LAS float* cw = (LAS float*)(lds + CONVW_OFF);
;               for (int i = tid; i < 1536; i += NWAVES * 64) { const int part = i >> 9, j = (i >> 7) & 3, cc = i & 127; cw[i] = args.in[3][j * 1536 + part * 512 + h_ * 128 + cc]; } }
;             DnRaw R; dn_load_raw(R, (int)blockIdx.x, DNR, HALO, GBT, tid);
.LBB0_319:
	v_mov_b32_e32 v2, v1
	v_lshl_add_u64 v[6:7], v[2:3], 2, s[22:23]
	v_add_u32_e32 v2, 0x400, v1
	v_lshl_add_u64 v[8:9], v[2:3], 2, s[22:23]
	global_load_dword v10, v[6:7], off
	global_load_dword v11, v[6:7], off offset:2048
	global_load_dword v12, v[8:9], off
	s_waitcnt vmcnt(2)
	ds_write_b32 v4, v10
	s_waitcnt vmcnt(1)
	ds_write_b32 v4, v11 offset:2048
	s_waitcnt vmcnt(0)
	ds_write_b32 v4, v12 offset:4096
	s_or_b64 exec, exec, s[6:7]
	s_ashr_i32 s3, s2, 31
	s_lshl_b64 s[14:15], s[2:3], 16
	s_add_u32 s12, s62, s14
	s_addc_u32 s13, s63, s15
	s_ashr_i32 s33, s2, 2
	s_and_b32 s4, s2, 3
	s_and_b32 s6, s2, 0x1fc
	s_cmp_lg_u32 s6, 0
	s_cselect_b64 s[10:11], -1, 0
	s_add_i32 s6, s33, -1
	s_mul_hi_i32 s7, s6, 0x2400
	s_mulk_i32 s6, 0x2400
	s_add_u32 s6, s28, s6
	v_lshrrev_b32_e32 v1, 3, v0
	s_addc_u32 s7, s29, s7
	s_mul_i32 s8, s4, 0x300
	v_and_b32_e32 v44, 62, v1
	s_add_u32 s6, s6, s8
	s_addc_u32 s7, s7, 0
	v_lshlrev_b32_e32 v2, 3, v0
	v_cmp_gt_u32_e64 s[8:9], 3, v44
	s_mov_b64 s[16:17], 0
	s_and_saveexec_b64 s[22:23], s[8:9]
	s_xor_b64 s[22:23], exec, s[22:23]
	s_cbranch_execz .LBB0_325
	s_and_b64 vcc, exec, s[10:11]
	s_cbranch_vccz .LBB0_323
	v_mul_u32_u24_e32 v6, 0x600, v44
	s_mov_b64 s[16:17], -1
	s_branch .LBB0_324
